# up GEMM produces val tiles first and gate tiles last (gate, read 1.25x by ffn_conv, is the cache-resident half)
# speedup vs baseline: 1.0036x; 1.0036x over previous
; __device__ __forceinline__ int fresh_lane() { int l; asm volatile("v_mbcnt_lo_u32_b32 %0, -1, 0\n\tv_mbcnt_hi_u32_b32 %0, -1, %0" : "=v"(l)); return l; }
; #define PG8_STAGE(bufoff, gbase, voff) do { _Pragma("unroll") for (int _i = 0; _i < 2; ++_i) \
;         __builtin_amdgcn_global_load_lds((const unsigned*)((const char*)(gbase) + (voff)[_i]), (LAS unsigned*)(lds + (bufoff) + ldsw + _i * 8192), 16, 0, 0); } while (0)
; #define PG8_BAR __builtin_amdgcn_s_barrier()
;     __device__ __forceinline__ const char* a(const pg8::Unit& u) const { return (const char*)ws + aoff + (size_t)u.pm * 256 * K_ * 2 + (u.kq < 0 ? 0 : u.kq * (K_ / 4) * 2); }
;     __device__ __forceinline__ bool next(int i, pg8::Unit& u) const { return pg8::tile2d<44>(i, nM, u); }
; template <class Epi, class Sched, bool ALIGN_EPI>
; __device__ __forceinline__ void gemm_phase(LAS unsigned char* lds, const int wid, const int lda_, const int ldb_, const int K_, const Sched& S, const Epi& E) {
;     ...
;     const int lane = fresh_lane(), tid = wid * 64 + lane;
;     const int wr = wid >> 2, wc = wid & 3, fr = lane & 15, fq = lane >> 4;
;     unsigned voffA[2], voffB[2];
; #pragma unroll
;     for (int i = 0; i < 2; ++i) { int R, C; stage_rc(tid * 16 + i * 8192, R, C); const int Rb = Epi::PERM ? ((R & ~31) + perm32(R & 31)) : R;
;         voffA[i] = (unsigned)(R * lda + C) * 2u; voffB[i] = (unsigned)(Rb * ldb + C) * 2u; }
;     const size_t kstep = (size_t)(BK * 2);
;     const size_t hstepA = (size_t)HALF * lda * 2, hstepB = (size_t)HALF * ldb * 2;
;     const unsigned ldsw = (unsigned)wid * 1024u;
;     const int aoff = lds_byte(wr * 64 + fr, fq * 8), boff = lds_byte(wc * 32 + fr, fq * 8);
;     ...
;     Unit cur, nxt; int ui = 0;
;     if (!S.next(0, cur)) return;
;     f32x4 acc[2][2][4][2];
; #pragma unroll
;     for (int a = 0; a < 2; ++a)
; #pragma unroll
;         for (int b = 0; b < 2; ++b)
; #pragma unroll
;             for (int m = 0; m < 4; ++m)
; #pragma unroll
;                 for (int n = 0; n < 2; ++n) acc[a][b][m][n] = (f32x4){0.f, 0.f, 0.f, 0.f};
;     bf16x8 At[4][2], B0[2][2], B1[2][2];
;     const char* cA = S.a(cur); const char* cB = S.b(cur);
;     PG8_STAGE(PG8_SB(0, 0), cB, voffB); PG8_STAGE(PG8_SB(0, 1), cB + hstepB, voffB); PG8_STAGE(PG8_SA(0, 0), cA, voffA); PG8_STAGE(PG8_SA(0, 1), cA + hstepA, voffA);
;     if (wr == 1) PG8_BAR;
.LBB0_1112:
	s_andn2_b64 vcc, exec, s[0:1]
	s_cbranch_vccnz .LBB0_1200
	v_readlane_b32 s0, v255, 35
	s_lshr_b32 s6, s0, 8
	s_mul_i32 s0, s6, 44
	s_cmp_ge_i32 s2, s0
	s_movk_i32 s34, 0x800
	s_movk_i32 s4, 0x800
	s_waitcnt vmcnt(0)
	v_mbcnt_lo_u32_b32 v0, -1, 0
	v_mbcnt_hi_u32_b32 v0, -1, v0
	v_mbcnt_lo_u32_b32 v6, -1, 0
	v_mbcnt_hi_u32_b32 v6, -1, v6
	s_cbranch_scc1 .LBB0_1125
	v_lshl_add_u32 v3, v6, 4, s3
	v_add_u32_e32 v0, 0x2000, v3
	v_ashrrev_i32_e32 v1, 31, v0
	v_lshrrev_b32_e32 v1, 22, v1
	v_add_u32_e32 v1, v0, v1
	v_ashrrev_i32_e32 v1, 10, v1
	v_mul_i32_i24_e32 v2, 0x400, v1
	v_sub_u32_e32 v0, v0, v2
	v_lshrrev_b32_e32 v2, 4, v0
	s_lshr_b32 s7, s0, 3
	v_bitop3_b32 v2, v2, v0, 32 bitop3:0x6c
	s_mul_i32 s5, s82, 0x2c00000
	s_or_b32 s14, s7, 1
	v_ashrrev_i32_e32 v0, 31, v2
	s_add_u32 s5, s66, s5
	v_lshrrev_b32_e32 v0, 26, v0
	s_addc_u32 s10, s67, 0
	v_add_u32_e32 v4, v2, v0
	v_lshlrev_b32_e32 v5, 3, v1
	s_add_u32 s15, s5, 0x9600000
	v_ashrrev_i32_e32 v0, 6, v4
	v_and_b32_e32 v5, -16, v5
	s_addc_u32 s26, s10, 0
	s_ashr_i32 s5, s4, 31
	v_add_u32_e32 v5, v0, v5
	s_lshl_b64 s[30:31], s[4:5], 8
	v_and_b32_e32 v0, 3, v0
	s_mov_b32 s5, 0x7fffffe0
	v_lshrrev_b32_e32 v7, 2, v5
	v_lshlrev_b32_e32 v8, 1, v5
	v_and_or_b32 v0, v5, s5, v0
	v_and_b32_e32 v7, 4, v7
	v_and_b32_e32 v8, 24, v8
	v_or3_b32 v0, v0, v7, v8
	v_mul_lo_u32 v7, v0, s4
	v_lshlrev_b32_e32 v0, 5, v1
	v_and_b32_e32 v1, 0xffc0, v4
	v_sub_u32_e32 v1, v2, v1
	v_lshrrev_b16_e32 v2, 7, v1
	v_and_b32_e32 v2, 1, v2
	v_add_u16_e32 v1, v1, v2
	v_ashrrev_i16_sdwa v1, v239, sext(v1) dst_sel:DWORD dst_unused:UNUSED_PAD src0_sel:DWORD src1_sel:BYTE_0
	v_and_b32_e32 v0, 32, v0
	v_bfe_i32 v1, v1, 0, 16
	v_add_u32_e32 v4, v0, v1
	v_mul_lo_u32 v2, v5, s34
	v_add_lshl_u32 v128, v7, v4, 1
	v_add_lshl_u32 v130, v4, v2, 1
	v_ashrrev_i32_e32 v4, 31, v3
	v_lshrrev_b32_e32 v4, 22, v4
	v_add_u32_e32 v4, v3, v4
	v_ashrrev_i32_e32 v4, 10, v4
	v_mul_i32_i24_e32 v5, 0x400, v4
	v_sub_u32_e32 v3, v3, v5
	v_lshrrev_b32_e32 v5, 4, v3
	v_bitop3_b32 v5, v5, v3, 32 bitop3:0x6c
	v_ashrrev_i32_e32 v3, 31, v5
	v_lshrrev_b32_e32 v3, 26, v3
	v_add_u32_e32 v7, v5, v3
	v_lshlrev_b32_e32 v8, 3, v4
	v_ashrrev_i32_e32 v3, 6, v7
	v_and_b32_e32 v8, -16, v8
	v_add_u32_e32 v8, v3, v8
	v_and_b32_e32 v3, 3, v3
	v_lshrrev_b32_e32 v9, 2, v8
	v_lshlrev_b32_e32 v10, 1, v8
	v_and_or_b32 v3, v8, s5, v3
	v_and_b32_e32 v9, 4, v9
	v_and_b32_e32 v10, 24, v10
	v_or3_b32 v3, v3, v9, v10
	s_ashr_i32 s35, s34, 31
	v_mul_lo_u32 v9, v3, s4
	v_readlane_b32 s4, v252, 55
	s_lshl_b64 s[10:11], s[34:35], 8
	v_readlane_b32 s5, v252, 56
	s_and_b64 s[4:5], s[4:5], exec
	s_cselect_b32 s4, s14, s7
	v_readlane_b32 s5, v253, 0
	s_mul_i32 s4, s4, s5
	v_readlane_b32 s5, v253, 56
	s_add_i32 s4, s4, s5
	s_mul_hi_i32 s5, s4, 0x2e8ba2e9
	s_lshr_b32 s17, s5, 31
	s_ashr_i32 s5, s5, 6
	s_add_i32 s5, s5, s17
	s_lshl_b32 s17, s5, 3
	s_sub_i32 s27, s6, s17
	s_min_i32 s27, s27, 8
	v_lshlrev_b32_e32 v3, 5, v4
	v_and_b32_e32 v4, 0xc0, v7
	s_abs_i32 s35, s27
	v_sub_u32_e32 v4, v5, v4
	v_cvt_f32_u32_e32 v10, s35
	v_ashrrev_i16_sdwa v4, v239, sext(v4) dst_sel:DWORD dst_unused:UNUSED_PAD src0_sel:DWORD src1_sel:BYTE_0
	v_and_b32_e32 v3, 32, v3
	v_bfe_i32 v4, v4, 0, 16
	v_add_u32_e32 v7, v3, v4
	v_mul_lo_u32 v5, v8, s34
	v_add_lshl_u32 v176, v9, v7, 1
	v_add_lshl_u32 v132, v7, v5, 1
	v_rcp_iflag_f32_e32 v7, v10
	s_sub_i32 s36, 0, s35
	s_mulk_i32 s5, 0x160
	s_sub_i32 s4, s4, s5
	v_mul_f32_e32 v7, 0x4f7ffffe, v7
	v_cvt_u32_f32_e32 v7, v7
	s_abs_i32 s34, s4
	s_xor_b32 s5, s4, s27
	s_ashr_i32 s5, s5, 31
	v_readfirstlane_b32 s37, v7
	s_mul_i32 s36, s36, s37
	s_mul_hi_u32 s36, s37, s36
	s_add_i32 s37, s37, s36
	s_mul_hi_u32 s36, s34, s37
	s_mul_i32 s37, s36, s35
	s_sub_i32 s34, s34, s37
	s_add_i32 s37, s36, 1
	s_sub_i32 s38, s34, s35
	s_cmp_ge_u32 s34, s35
	s_cselect_b32 s36, s37, s36
	s_cselect_b32 s34, s38, s34
	s_add_i32 s37, s36, 1
	s_cmp_ge_u32 s34, s35
	s_cselect_b32 s34, s37, s36
	s_xor_b32 s34, s34, s5
	s_sub_i32 s38, s34, s5
	s_mul_i32 s5, s38, s27
	s_sub_i32 s4, s4, s5
	s_add_i32 s34, s17, s4
	s_add_i32 s38, s38, 22
	s_cmp_ge_i32 s38, 44
	s_cselect_b32 s100, 44, 0
	s_sub_i32 s38, s38, s100
	s_ashr_i32 s35, s34, 31
	s_ashr_i32 s39, s38, 31
	s_lshl_b64 s[36:37], s[34:35], 20
	s_lshl_b64 s[4:5], s[38:39], 20
	s_add_u32 s50, s15, s4
	s_addc_u32 s51, s26, s5
	s_add_i32 m0, s16, 0x10000
	v_readlane_b32 s40, v253, 52
	global_load_lds_dwordx4 v176, s[50:51]
	s_add_i32 m0, s16, 0x12000
	s_add_u32 s4, s50, s30
	global_load_lds_dwordx4 v128, s[50:51]
	s_addc_u32 s5, s51, s31
	s_add_i32 m0, s16, 0x14000
	v_readlane_b32 s41, v253, 53
	global_load_lds_dwordx4 v176, s[4:5]
	s_add_i32 m0, s16, 0x16000
	s_add_u32 s40, s40, s36
	s_addc_u32 s41, s41, s37
	s_add_i32 s35, s16, 0x2000
	global_load_lds_dwordx4 v128, s[4:5]
	s_mov_b32 m0, s16
	s_add_u32 s36, s40, s10
	global_load_lds_dwordx4 v132, s[40:41]
	s_mov_b32 m0, s35
	s_addc_u32 s37, s41, s11
	s_add_i32 s39, s16, 0x4000
	global_load_lds_dwordx4 v130, s[40:41]
	s_mov_b32 m0, s39
	s_add_i32 s72, s16, 0x6000
	global_load_lds_dwordx4 v132, s[36:37]
	s_mov_b32 m0, s72
	s_mov_b32 s1, s92
	global_load_lds_dwordx4 v130, s[36:37]
	v_readlane_b32 s36, v252, 58
	v_readlane_b32 s37, v252, 59
	s_andn2_b64 vcc, exec, s[36:37]
	s_cbranch_vccnz .LBB0_1116
	s_barrier

;     __device__ __forceinline__ bool next(int i, pg8::Unit& u) const { return pg8::tile2d<72>(i, 16, u); }
; template <int NN> __device__ __forceinline__ bool tile2d(int i, int nM, Unit& u) {
;     const long L = (long)i * (int)gridDim.x + (int)blockIdx.x; if (L >= nM * NN) return false;
;     tile_of_id<NN>((int)L, nM, u.pm, u.pn); u.kq = -1; return true;
;     __device__ __forceinline__ bool next(int i, pg8::Unit& u) const { return pg8::tile2d<44>(i, nM, u); }
.LBB0_1117:
	s_add_i32 s75, s75, 1
	s_mul_i32 s4, s91, s75
	s_mul_hi_u32 s5, s90, s75
	s_add_i32 s5, s5, s4
	s_mul_i32 s4, s90, s75
	s_add_u32 s4, s4, s2
	v_readlane_b32 s17, v252, 52
	s_addc_u32 s5, s5, s17
	v_mov_b64_e32 v[0:1], s[0:1]
	v_cmp_ge_i64_e64 s[36:37], s[4:5], v[0:1]
	s_and_b64 vcc, exec, s[36:37]
	s_cbranch_vccnz .LBB0_1119
	s_ashr_i32 s17, s4, 31
	s_lshr_b32 s17, s17, 29
	s_add_i32 s17, s4, s17
	s_ashr_i32 s27, s17, 3
	s_and_b32 s17, s17, -8
	s_sub_i32 s17, s4, s17
	s_cmp_lt_i32 s17, 0
	s_cselect_b32 s42, s14, s7
	s_mul_i32 s17, s42, s17
	s_add_i32 s17, s17, s27
	s_mul_hi_i32 s27, s17, 0x2e8ba2e9
	s_lshr_b32 s42, s27, 31
	s_ashr_i32 s27, s27, 6
	s_add_i32 s27, s27, s42
	s_lshl_b32 s43, s27, 3
	s_sub_i32 s42, s6, s43
	s_min_i32 s44, s42, 8
	s_abs_i32 s42, s44
	v_cvt_f32_u32_e32 v0, s42
	s_sub_i32 s46, 0, s42
	s_mulk_i32 s27, 0x160
	s_sub_i32 s17, s17, s27
	v_rcp_iflag_f32_e32 v0, v0
	s_abs_i32 s27, s17
	s_xor_b32 s45, s17, s44
	s_ashr_i32 s45, s45, 31
	v_mul_f32_e32 v0, 0x4f7ffffe, v0
	v_cvt_u32_f32_e32 v0, v0
	s_nop 0
	v_readfirstlane_b32 s47, v0
	s_mul_i32 s46, s46, s47
	s_mul_hi_u32 s46, s47, s46
	s_add_i32 s47, s47, s46
	s_mul_hi_u32 s46, s27, s47
	s_mul_i32 s47, s46, s42
	s_sub_i32 s27, s27, s47
	s_add_i32 s48, s46, 1
	s_sub_i32 s47, s27, s42
	s_cmp_ge_u32 s27, s42
	s_cselect_b32 s46, s48, s46
	s_cselect_b32 s27, s47, s27
	s_add_i32 s47, s46, 1
	s_cmp_ge_u32 s27, s42
	s_cselect_b32 s27, s47, s46
	s_xor_b32 s27, s27, s45
	s_sub_i32 s42, s27, s45
	s_mul_i32 s27, s42, s44
	s_sub_i32 s17, s17, s27
	s_add_i32 s44, s17, s43
	s_add_i32 s42, s42, 22
	s_cmp_ge_i32 s42, 44
	s_cselect_b32 s100, 44, 0
	s_sub_i32 s42, s42, s100
